# P0->P1 seam: the cooperative-groups grid.sync (every workgroup flushes L2) replaced by a copy of the kernel's own XCD-hierarchical barrier (one L2 writeback per XCD)
# speedup vs baseline: 1.0007x; 1.0007x over previous
; __device__ __forceinline__ void xcd_barrier(const XcdBarrier& b) {
;     asm volatile("s_waitcnt vmcnt(0)" ::: "memory");
;     __syncthreads();
;     if (threadIdx.x == 0) {
.Lgsync_473:
	s_waitcnt vmcnt(0)
	s_barrier
	s_mov_b64 s[0:1], exec
	v_readlane_b32 s2, v254, 17
	v_readlane_b32 s3, v254, 18
	s_and_b64 s[2:3], s[0:1], s[2:3]
	s_mov_b64 exec, s[2:3]
	s_cbranch_execz .Lgsync_525

; __device__ __forceinline__ void xcd_barrier(const XcdBarrier& b) {
;     ...
;         unsigned nloc = b.st[0], nx = b.st[1];
;         if (nloc == 0u) { xcd_barrier_complete(bar, b.x, nloc, nx); b.st[0] = nloc; b.st[1] = nx; }
	s_add_i32 s2, 0, 0x21040
	v_mov_b32_e32 v0, s2
	s_waitcnt vmcnt(0) expcnt(0) lgkmcnt(0)
	ds_read_b32 v2, v0
	s_add_i32 s2, 0, 0x21044
	v_mov_b32_e32 v0, s2
	ds_read_b32 v0, v0
	s_waitcnt lgkmcnt(1)
	v_cmp_ne_u32_e32 vcc, 0, v2
	s_cbranch_vccnz .Lgsync_489

; __device__ __forceinline__ unsigned xb_ld(unsigned* p)              { return __hip_atomic_load(p, __ATOMIC_RELAXED, __HIP_MEMORY_SCOPE_AGENT); }
; __device__ __forceinline__ void xcd_barrier_complete(unsigned* bar, unsigned x, unsigned& nloc, unsigned& nx) {
;     const unsigned G = gridDim.x * gridDim.y * gridDim.z;
;     unsigned sum, cnt, mine, sp = 0u;
;     for (;;) {
;         sum = 0u; cnt = 0u; mine = 0u;
; #pragma unroll
;         for (unsigned j = 0; j < 16; ++j) { const unsigned c = xb_ld(&bar[XB_XCNT(j)]); sum += c; cnt += (c > 0u) ? 1u : 0u; mine = (j == x) ? c : mine; }
;         if (sum == G) break;
;         __builtin_amdgcn_s_sleep(1);
;         if ((++sp & 255u) == 0u) { if (xb_ld(&bar[XB_TMO])) break; if (sp > XB_SPIN_CAP) { atomicAdd(&bar[XB_TMO], 1u); break; } }
;     }
;     nloc = mine > 0u ? mine : 1u; nx = cnt > 0u ? cnt : 1u;
	v_readlane_b32 s48, v254, 9
	v_readlane_b32 s51, v254, 12
	v_readlane_b32 s2, v254, 13
	v_readlane_b32 s49, v254, 10
	s_mul_i32 s33, s51, s2
	s_add_u32 s2, s48, 0x190200
	s_addc_u32 s3, s49, 0
	s_add_u32 s4, s48, 0x190400
	s_addc_u32 s5, s49, 0
	s_add_u32 s6, s48, 0x190500
	s_addc_u32 s7, s49, 0
	s_add_u32 s8, s48, 0x190600
	s_addc_u32 s9, s49, 0
	s_add_u32 s10, s48, 0x190700
	s_addc_u32 s11, s49, 0
	s_add_u32 s12, s48, 0x190800
	s_addc_u32 s13, s49, 0
	s_add_u32 s14, s48, 0x190900
	s_addc_u32 s15, s49, 0
	s_add_u32 s16, s48, 0x190a00
	s_addc_u32 s17, s49, 0
	s_add_u32 s18, s48, 0x190b00
	s_addc_u32 s19, s49, 0
	s_add_u32 s28, s48, 0x190c00
	s_addc_u32 s29, s49, 0
	s_add_u32 s30, s48, 0x190d00
	s_addc_u32 s31, s49, 0
	s_add_u32 s38, s48, 0x190e00
	s_addc_u32 s39, s49, 0
	s_add_u32 s40, s48, 0x190f00
	s_addc_u32 s41, s49, 0
	s_add_u32 s42, s48, 0x191000
	s_addc_u32 s43, s49, 0
	s_add_u32 s44, s48, 0x191100
	s_addc_u32 s45, s49, 0
	s_add_u32 s46, s48, 0x191200
	s_addc_u32 s47, s49, 0
	v_readlane_b32 s50, v254, 11
	s_add_u32 s48, s48, 0x191300
	s_mul_i32 s33, s33, s50
	s_addc_u32 s49, s49, 0
	s_mov_b32 s56, 1
	v_mov_b32_e32 v16, 0
	s_branch .Lgsync_477

; __device__ __forceinline__ unsigned xb_ld(unsigned* p)              { return __hip_atomic_load(p, __ATOMIC_RELAXED, __HIP_MEMORY_SCOPE_AGENT); }
; __device__ __forceinline__ void xcd_barrier_complete(unsigned* bar, unsigned x, unsigned& nloc, unsigned& nx) {
;     ...
;     for (;;) {
;         sum = 0u; cnt = 0u; mine = 0u;
; #pragma unroll
;         for (unsigned j = 0; j < 16; ++j) { const unsigned c = xb_ld(&bar[XB_XCNT(j)]); sum += c; cnt += (c > 0u) ? 1u : 0u; mine = (j == x) ? c : mine; }
;         if (sum == G) break;
.Lgsync_477:
	global_load_dword v15, v16, s[4:5] sc1
	s_waitcnt lgkmcnt(0)
	global_load_dword v0, v16, s[6:7] sc1
	global_load_dword v1, v16, s[8:9] sc1
	global_load_dword v2, v16, s[10:11] sc1
	global_load_dword v3, v16, s[12:13] sc1
	global_load_dword v4, v16, s[14:15] sc1
	global_load_dword v5, v16, s[16:17] sc1
	global_load_dword v6, v16, s[18:19] sc1
	global_load_dword v7, v16, s[28:29] sc1
	global_load_dword v8, v16, s[30:31] sc1
	global_load_dword v9, v16, s[38:39] sc1
	global_load_dword v10, v16, s[40:41] sc1
	global_load_dword v11, v16, s[42:43] sc1
	global_load_dword v12, v16, s[44:45] sc1
	global_load_dword v13, v16, s[46:47] sc1
	global_load_dword v14, v16, s[48:49] sc1
	s_mov_b64 s[50:51], -1
	s_mov_b64 s[52:53], -1
	s_waitcnt vmcnt(14)
	v_add_u32_e32 v17, v0, v15
	s_waitcnt vmcnt(13)
	v_add_u32_e32 v17, v17, v1
	s_waitcnt vmcnt(12)
	v_add_u32_e32 v17, v17, v2
	s_waitcnt vmcnt(11)
	v_add_u32_e32 v17, v17, v3
	s_waitcnt vmcnt(10)
	v_add_u32_e32 v17, v17, v4
	s_waitcnt vmcnt(9)
	v_add_u32_e32 v17, v17, v5
	s_waitcnt vmcnt(8)
	v_add_u32_e32 v17, v17, v6
	s_waitcnt vmcnt(7)
	v_add_u32_e32 v17, v17, v7
	s_waitcnt vmcnt(6)
	v_add_u32_e32 v17, v17, v8
	s_waitcnt vmcnt(5)
	v_add_u32_e32 v17, v17, v9
	s_waitcnt vmcnt(4)
	v_add_u32_e32 v17, v17, v10
	s_waitcnt vmcnt(3)
	v_add_u32_e32 v17, v17, v11
	s_waitcnt vmcnt(2)
	v_add_u32_e32 v17, v17, v12
	s_waitcnt vmcnt(1)
	v_add_u32_e32 v17, v17, v13
	s_waitcnt vmcnt(0)
	v_add_u32_e32 v17, v17, v14
	v_cmp_eq_u32_e32 vcc, s33, v17
	s_cbranch_vccnz .Lgsync_476

; __device__ __forceinline__ unsigned xb_ld(unsigned* p)              { return __hip_atomic_load(p, __ATOMIC_RELAXED, __HIP_MEMORY_SCOPE_AGENT); }
; __device__ __forceinline__ void xcd_barrier_complete(unsigned* bar, unsigned x, unsigned& nloc, unsigned& nx) {
;     ...
;         __builtin_amdgcn_s_sleep(1);
;         if ((++sp & 255u) == 0u) { if (xb_ld(&bar[XB_TMO])) break; if (sp > XB_SPIN_CAP) { atomicAdd(&bar[XB_TMO], 1u); break; } }
	s_and_b32 s50, s56, 0xff
	s_cmp_eq_u32 s50, 0
	s_mov_b64 s[50:51], -1
	s_mov_b64 s[54:55], -1
	s_sleep 1
	s_cbranch_scc0 .Lgsync_481

; __device__ __forceinline__ unsigned xb_ld(unsigned* p)              { return __hip_atomic_load(p, __ATOMIC_RELAXED, __HIP_MEMORY_SCOPE_AGENT); }
; __device__ __forceinline__ void xcd_barrier_complete(unsigned* bar, unsigned x, unsigned& nloc, unsigned& nx) {
;     ...
;         if ((++sp & 255u) == 0u) { if (xb_ld(&bar[XB_TMO])) break; if (sp > XB_SPIN_CAP) { atomicAdd(&bar[XB_TMO], 1u); break; } }
	global_load_dword v17, v16, s[2:3] sc1
	s_waitcnt vmcnt(0)
	v_cmp_eq_u32_e32 vcc, 0, v17
	s_cbranch_vccnz .Lgsync_483

; __device__ __forceinline__ unsigned xb_ld(unsigned* p)              { return __hip_atomic_load(p, __ATOMIC_RELAXED, __HIP_MEMORY_SCOPE_AGENT); }
; __device__ __forceinline__ void xcd_barrier_complete(unsigned* bar, unsigned x, unsigned& nloc, unsigned& nx) {
;     ...
;         if ((++sp & 255u) == 0u) { if (xb_ld(&bar[XB_TMO])) break; if (sp > XB_SPIN_CAP) { atomicAdd(&bar[XB_TMO], 1u); break; } }
	s_mov_b64 s[54:55], 0

; __device__ __forceinline__ unsigned xb_ld(unsigned* p)              { return __hip_atomic_load(p, __ATOMIC_RELAXED, __HIP_MEMORY_SCOPE_AGENT); }
; __device__ __forceinline__ void xcd_barrier_complete(unsigned* bar, unsigned x, unsigned& nloc, unsigned& nx) {
;     ...
;     for (;;) {
;         sum = 0u; cnt = 0u; mine = 0u;
; #pragma unroll
;         for (unsigned j = 0; j < 16; ++j) { const unsigned c = xb_ld(&bar[XB_XCNT(j)]); sum += c; cnt += (c > 0u) ? 1u : 0u; mine = (j == x) ? c : mine; }
;         if (sum == G) break;
;         __builtin_amdgcn_s_sleep(1);
;         if ((++sp & 255u) == 0u) { if (xb_ld(&bar[XB_TMO])) break; if (sp > XB_SPIN_CAP) { atomicAdd(&bar[XB_TMO], 1u); break; } }
;     }
;     nloc = mine > 0u ? mine : 1u; nx = cnt > 0u ? cnt : 1u;
.Lgsync_484:
	s_andn2_b64 vcc, exec, s[50:51]
	s_cbranch_vccz .Lgsync_488

; __device__ __forceinline__ unsigned xb_ld(unsigned* p)              { return __hip_atomic_load(p, __ATOMIC_RELAXED, __HIP_MEMORY_SCOPE_AGENT); }
; __device__ __forceinline__ void xcd_barrier_complete(unsigned* bar, unsigned x, unsigned& nloc, unsigned& nx) {
;     ...
;         if ((++sp & 255u) == 0u) { if (xb_ld(&bar[XB_TMO])) break; if (sp > XB_SPIN_CAP) { atomicAdd(&bar[XB_TMO], 1u); break; } }
	s_mov_b64 s[6:7], exec
	v_mbcnt_lo_u32_b32 v16, s6, 0
	v_mbcnt_hi_u32_b32 v16, s7, v16
	v_cmp_eq_u32_e32 vcc, 0, v16
	s_and_saveexec_b64 s[4:5], vcc
	s_cbranch_execz .Lgsync_487

; __device__ __forceinline__ unsigned xb_ld(unsigned* p)              { return __hip_atomic_load(p, __ATOMIC_RELAXED, __HIP_MEMORY_SCOPE_AGENT); }
; __device__ __forceinline__ void xcd_barrier_complete(unsigned* bar, unsigned x, unsigned& nloc, unsigned& nx) {
;     ...
;         if ((++sp & 255u) == 0u) { if (xb_ld(&bar[XB_TMO])) break; if (sp > XB_SPIN_CAP) { atomicAdd(&bar[XB_TMO], 1u); break; } }
	s_bcnt1_i32_b64 s6, s[6:7]
	v_mov_b32_e32 v16, 0
	v_mov_b32_e32 v17, s6
	global_atomic_add v16, v17, s[2:3]

; __device__ __forceinline__ unsigned xb_add(unsigned* p, unsigned v) { return __hip_atomic_fetch_add(p, v, __ATOMIC_RELAXED, __HIP_MEMORY_SCOPE_AGENT); }
; __device__ __forceinline__ void xcd_barrier(const XcdBarrier& b) {
;     ...
;         unsigned nloc = b.st[0], nx = b.st[1];
;         if (nloc == 0u) { xcd_barrier_complete(bar, b.x, nloc, nx); b.st[0] = nloc; b.st[1] = nx; }
;         const unsigned old = xb_add(&bar[XB_XSUB(b.x)], 1u);
.Lgsync_489:
	s_mov_b64 s[4:5], exec
	v_readlane_b32 s2, v254, 16
	s_lshl_b32 s2, s2, 8
	v_readlane_b32 s6, v254, 14
	v_mbcnt_lo_u32_b32 v1, s4, 0
	v_readlane_b32 s7, v254, 15
	s_add_u32 s2, s6, s2
	v_mbcnt_hi_u32_b32 v1, s5, v1
	s_addc_u32 s3, s7, 0
	v_cmp_eq_u32_e32 vcc, 0, v1

; __device__ __forceinline__ unsigned xb_add(unsigned* p, unsigned v) { return __hip_atomic_fetch_add(p, v, __ATOMIC_RELAXED, __HIP_MEMORY_SCOPE_AGENT); }
; __device__ __forceinline__ void xcd_barrier(const XcdBarrier& b) {
;     ...
;         const unsigned old = xb_add(&bar[XB_XSUB(b.x)], 1u);
	s_and_saveexec_b64 s[6:7], vcc
	s_cbranch_execz .Lgsync_491

; __device__ __forceinline__ unsigned xb_add(unsigned* p, unsigned v) { return __hip_atomic_fetch_add(p, v, __ATOMIC_RELAXED, __HIP_MEMORY_SCOPE_AGENT); }
; __device__ __forceinline__ void xcd_barrier(const XcdBarrier& b) {
;     ...
;         const unsigned old = xb_add(&bar[XB_XSUB(b.x)], 1u);
;         const unsigned gen = old / nloc;
;         if (old + 1u == (gen + 1u) * nloc) {
	s_bcnt1_i32_b64 s4, s[4:5]
	v_mov_b32_e32 v3, 0x1000
	v_mov_b32_e32 v4, s4
	global_atomic_add v3, v3, v4, s[2:3] offset:1024 sc0
.Lgsync_491:
	s_or_b64 exec, exec, s[6:7]
	v_cvt_f32_u32_e32 v4, v2
	s_waitcnt vmcnt(0)
	v_readfirstlane_b32 s4, v3
	v_sub_u32_e32 v3, 0, v2
	v_rcp_iflag_f32_e32 v4, v4
	v_add_u32_e32 v5, s4, v1
	v_mul_f32_e32 v4, 0x4f7ffffe, v4
	v_cvt_u32_f32_e32 v4, v4
	v_mul_lo_u32 v1, v3, v4
	v_mul_hi_u32 v1, v4, v1
	v_add_u32_e32 v1, v4, v1
	v_mul_hi_u32 v1, v5, v1
	v_mul_lo_u32 v3, v1, v2
	v_sub_u32_e32 v3, v5, v3
	v_add_u32_e32 v4, 1, v1
	v_cmp_ge_u32_e32 vcc, v3, v2
	s_nop 1
	v_cndmask_b32_e32 v1, v1, v4, vcc
	v_sub_u32_e32 v4, v3, v2
	v_cndmask_b32_e32 v3, v3, v4, vcc
	v_add_u32_e32 v4, 1, v1
	v_cmp_ge_u32_e32 vcc, v3, v2
	v_add_u32_e32 v3, 1, v5
	s_nop 0
	v_cndmask_b32_e32 v1, v1, v4, vcc
	v_mul_lo_u32 v4, v2, v1
	v_add_u32_e32 v2, v4, v2
	v_cmp_ne_u32_e32 vcc, v3, v2
	s_and_saveexec_b64 s[4:5], vcc
	s_xor_b64 s[4:5], exec, s[4:5]
	s_cbranch_execz .Lgsync_505

; __device__ __forceinline__ unsigned xb_ld(unsigned* p)              { return __hip_atomic_load(p, __ATOMIC_RELAXED, __HIP_MEMORY_SCOPE_AGENT); }
; #define XB_SPIN(cond, bar) do { unsigned _sp = 0; while (cond) { __builtin_amdgcn_s_sleep(1); \
;     if ((++_sp & 255u) == 0u) { if (xb_ld(&(bar)[XB_TMO])) break; if (_sp > XB_SPIN_CAP) { atomicAdd(&(bar)[XB_TMO], 1u); break; } } } } while (0)
; __device__ __forceinline__ void xcd_barrier(const XcdBarrier& b) {
;     ...
;             XB_SPIN(xb_ld(&bar[XB_XGEN(b.x)]) == gen, bar);
	s_waitcnt lgkmcnt(0)
	v_mov_b32_e32 v0, 0x2000
	global_load_dword v0, v0, s[2:3] offset:1024 sc1
	s_add_u32 s10, s2, 0x2400
	s_addc_u32 s11, s3, 0
	s_waitcnt vmcnt(0)
	v_cmp_eq_u32_e32 vcc, v0, v1
	s_and_saveexec_b64 s[6:7], vcc
	s_cbranch_execz .Lgsync_504

	v_readlane_b32 s12, v254, 9
	v_readlane_b32 s13, v254, 10
	s_add_u32 s8, s12, 0x190200
	v_readlane_b32 s14, v254, 11
	v_readlane_b32 s15, v254, 12
	s_addc_u32 s9, s13, 0
	s_mov_b32 s30, 1
	s_mov_b64 s[12:13], 0
	v_mov_b32_e32 v0, 0

; __device__ __forceinline__ unsigned xb_ld(unsigned* p)              { return __hip_atomic_load(p, __ATOMIC_RELAXED, __HIP_MEMORY_SCOPE_AGENT); }
; #define XB_SPIN(cond, bar) do { unsigned _sp = 0; while (cond) { __builtin_amdgcn_s_sleep(1); \
;     if ((++_sp & 255u) == 0u) { if (xb_ld(&(bar)[XB_TMO])) break; if (_sp > XB_SPIN_CAP) { atomicAdd(&(bar)[XB_TMO], 1u); break; } } } } while (0)
; __device__ __forceinline__ void xcd_barrier(const XcdBarrier& b) {
;     ...
;             XB_SPIN(xb_ld(&bar[XB_XGEN(b.x)]) == gen, bar);
	s_branch .Lgsync_495

.Lgsync_495:
	s_and_b32 s18, s30, 0xff
	s_mov_b64 s[16:17], -1
	s_cmp_lg_u32 s18, 0
	s_mov_b64 s[28:29], -1
	s_sleep 1

	s_cbranch_scc1 .Lgsync_498

	global_load_dword v2, v0, s[8:9] sc1
	s_waitcnt vmcnt(0)
	v_cmp_eq_u32_e32 vcc, 0, v2
	s_cbranch_vccnz .Lgsync_500

	s_mov_b64 s[28:29], 0
	s_mov_b64 s[18:19], -1

.Lgsync_501:
	s_or_b64 exec, exec, s[12:13]
	s_xor_b64 s[10:11], s[14:15], -1
	s_and_saveexec_b64 s[12:13], s[10:11]
	s_xor_b64 s[12:13], exec, s[12:13]
	s_cbranch_execz .Lgsync_504

	s_mov_b64 s[10:11], exec
	v_mbcnt_lo_u32_b32 v0, s10, 0
	v_mbcnt_hi_u32_b32 v0, s11, v0
	v_cmp_eq_u32_e32 vcc, 0, v0
	s_and_b64 s[12:13], exec, vcc
	s_mov_b64 exec, s[12:13]
	s_cbranch_execz .Lgsync_504

; __device__ __forceinline__ void xcd_barrier(const XcdBarrier& b) {
;     ...
;             __builtin_amdgcn_fence(__ATOMIC_ACQUIRE, "agent");
;             asm volatile("s_waitcnt vmcnt(0)" ::: "memory");
	s_bcnt1_i32_b64 s10, s[10:11]
	v_mov_b32_e32 v0, 0
	v_mov_b32_e32 v1, s10
	global_atomic_add v0, v1, s[8:9]
.Lgsync_504:
	s_or_b64 exec, exec, s[6:7]
	s_waitcnt vmcnt(0)
	buffer_inv sc1
	s_waitcnt vmcnt(0)

; __device__ __forceinline__ void xcd_barrier(const XcdBarrier& b) {
;     ...
;         if (old + 1u == (gen + 1u) * nloc) {
;             __builtin_amdgcn_fence(__ATOMIC_RELEASE, "agent");
.Lgsync_505:
	s_andn2_saveexec_b64 s[4:5], s[4:5]
	s_cbranch_execz .Lgsync_525

; __device__ __forceinline__ unsigned xb_add(unsigned* p, unsigned v) { return __hip_atomic_fetch_add(p, v, __ATOMIC_RELAXED, __HIP_MEMORY_SCOPE_AGENT); }
; __device__ __forceinline__ void xcd_barrier(const XcdBarrier& b) {
;     ...
;             __builtin_amdgcn_fence(__ATOMIC_RELEASE, "agent");
;             asm volatile("s_waitcnt vmcnt(0)" ::: "memory");
;             const unsigned og = xb_add(&bar[XB_TOP], 1u);
	s_mov_b64 s[4:5], exec
	buffer_wbl2 sc1
	s_waitcnt lgkmcnt(0)
	s_waitcnt vmcnt(0)
	v_mbcnt_lo_u32_b32 v1, s4, 0
	v_mbcnt_hi_u32_b32 v1, s5, v1
	v_cmp_eq_u32_e32 vcc, 0, v1

; __device__ __forceinline__ unsigned xb_add(unsigned* p, unsigned v) { return __hip_atomic_fetch_add(p, v, __ATOMIC_RELAXED, __HIP_MEMORY_SCOPE_AGENT); }
; __device__ __forceinline__ void xcd_barrier(const XcdBarrier& b) {
;     ...
;             const unsigned og = xb_add(&bar[XB_TOP], 1u);
	s_and_saveexec_b64 s[6:7], vcc
	s_cbranch_execz .Lgsync_508

; __device__ __forceinline__ unsigned xb_add(unsigned* p, unsigned v) { return __hip_atomic_fetch_add(p, v, __ATOMIC_RELAXED, __HIP_MEMORY_SCOPE_AGENT); }
; __device__ __forceinline__ void xcd_barrier(const XcdBarrier& b) {
;     ...
;             const unsigned og = xb_add(&bar[XB_TOP], 1u);
;             const unsigned tg = og / nx;
;             if (og + 1u == (tg + 1u) * nx) xb_add(&bar[XB_TOPGEN], 1u);
	s_bcnt1_i32_b64 s4, s[4:5]
	v_readlane_b32 s8, v254, 9
	v_mov_b32_e32 v2, 0x193000
	v_mov_b32_e32 v3, s4
	v_readlane_b32 s9, v254, 10
	v_readlane_b32 s10, v254, 11
	v_readlane_b32 s11, v254, 12
	s_nop 2
	global_atomic_add v2, v2, v3, s[8:9] offset:1024 sc0
.Lgsync_508:
	s_or_b64 exec, exec, s[6:7]
	v_cvt_f32_u32_e32 v3, v0
	s_waitcnt vmcnt(0)
	v_readfirstlane_b32 s4, v2
	s_mov_b64 s[8:9], -1
	v_rcp_iflag_f32_e32 v3, v3
	v_add_u32_e32 v1, s4, v1
	v_add_u32_e32 v4, 1, v1
	v_readlane_b32 s4, v254, 9
	v_mul_f32_e32 v2, 0x4f7ffffe, v3
	v_cvt_u32_f32_e32 v2, v2
	v_sub_u32_e32 v3, 0, v0
	v_readlane_b32 s6, v254, 11
	v_readlane_b32 s5, v254, 10
	v_mul_lo_u32 v3, v3, v2
	v_mul_hi_u32 v3, v2, v3
	v_add_u32_e32 v2, v2, v3
	v_mul_hi_u32 v2, v1, v2
	v_mul_lo_u32 v3, v2, v0
	v_sub_u32_e32 v1, v1, v3
	v_add_u32_e32 v5, 1, v2
	v_cmp_ge_u32_e32 vcc, v1, v0
	v_sub_u32_e32 v3, v1, v0
	v_readlane_b32 s7, v254, 12
	v_cndmask_b32_e32 v2, v2, v5, vcc
	v_cndmask_b32_e32 v1, v1, v3, vcc
	v_add_u32_e32 v3, 1, v2
	v_cmp_ge_u32_e32 vcc, v1, v0
	s_add_u32 s6, s4, 0x193500
	s_addc_u32 s7, s5, 0
	v_cndmask_b32_e32 v2, v2, v3, vcc
	v_mul_lo_u32 v1, v0, v2
	v_add_u32_e32 v0, v1, v0
	v_cmp_ne_u32_e32 vcc, v4, v0
	v_mov_b64_e32 v[0:1], s[6:7]
	s_and_saveexec_b64 s[4:5], vcc
	s_cbranch_execz .Lgsync_520

; __device__ __forceinline__ unsigned xb_ld(unsigned* p)              { return __hip_atomic_load(p, __ATOMIC_RELAXED, __HIP_MEMORY_SCOPE_AGENT); }
; #define XB_SPIN(cond, bar) do { unsigned _sp = 0; while (cond) { __builtin_amdgcn_s_sleep(1); \
;     if ((++_sp & 255u) == 0u) { if (xb_ld(&(bar)[XB_TMO])) break; if (_sp > XB_SPIN_CAP) { atomicAdd(&(bar)[XB_TMO], 1u); break; } } } } while (0)
; __device__ __forceinline__ void xcd_barrier(const XcdBarrier& b) {
;     ...
;             else XB_SPIN(xb_ld(&bar[XB_TOPGEN]) == tg, bar);
	v_mov_b32_e32 v0, 0
	global_load_dword v1, v0, s[6:7] sc1
	s_mov_b64 s[12:13], 0

; __device__ __forceinline__ unsigned xb_ld(unsigned* p)              { return __hip_atomic_load(p, __ATOMIC_RELAXED, __HIP_MEMORY_SCOPE_AGENT); }
; #define XB_SPIN(cond, bar) do { unsigned _sp = 0; while (cond) { __builtin_amdgcn_s_sleep(1); \
;     if ((++_sp & 255u) == 0u) { if (xb_ld(&(bar)[XB_TMO])) break; if (_sp > XB_SPIN_CAP) { atomicAdd(&(bar)[XB_TMO], 1u); break; } } } } while (0)
; __device__ __forceinline__ void xcd_barrier(const XcdBarrier& b) {
;     ...
;             else XB_SPIN(xb_ld(&bar[XB_TOPGEN]) == tg, bar);
	s_waitcnt vmcnt(0)
	v_cmp_eq_u32_e32 vcc, v1, v2
	s_and_saveexec_b64 s[10:11], vcc
	s_cbranch_execz .Lgsync_519

; __device__ __forceinline__ unsigned xb_ld(unsigned* p)              { return __hip_atomic_load(p, __ATOMIC_RELAXED, __HIP_MEMORY_SCOPE_AGENT); }
; #define XB_SPIN(cond, bar) do { unsigned _sp = 0; while (cond) { __builtin_amdgcn_s_sleep(1); \
;     if ((++_sp & 255u) == 0u) { if (xb_ld(&(bar)[XB_TMO])) break; if (_sp > XB_SPIN_CAP) { atomicAdd(&(bar)[XB_TMO], 1u); break; } } } } while (0)
; __device__ __forceinline__ void xcd_barrier(const XcdBarrier& b) {
;     ...
;             else XB_SPIN(xb_ld(&bar[XB_TOPGEN]) == tg, bar);
	v_readlane_b32 s12, v254, 9
	v_readlane_b32 s13, v254, 10
	s_add_u32 s8, s12, 0x190200
	v_readlane_b32 s14, v254, 11
	v_readlane_b32 s15, v254, 12
	s_addc_u32 s9, s13, 0
	s_mov_b32 s30, 1
	s_mov_b64 s[12:13], 0

; __device__ __forceinline__ unsigned xb_ld(unsigned* p)              { return __hip_atomic_load(p, __ATOMIC_RELAXED, __HIP_MEMORY_SCOPE_AGENT); }
; #define XB_SPIN(cond, bar) do { unsigned _sp = 0; while (cond) { __builtin_amdgcn_s_sleep(1); \
;     if ((++_sp & 255u) == 0u) { if (xb_ld(&(bar)[XB_TMO])) break; if (_sp > XB_SPIN_CAP) { atomicAdd(&(bar)[XB_TMO], 1u); break; } } } } while (0)
; __device__ __forceinline__ void xcd_barrier(const XcdBarrier& b) {
;     ...
;             else XB_SPIN(xb_ld(&bar[XB_TOPGEN]) == tg, bar);
	s_branch .Lgsync_512

.Lgsync_512:
	s_and_b32 s16, s30, 0xff
	s_cmp_lg_u32 s16, 0
	s_mov_b64 s[18:19], -1
	s_sleep 1

	s_cbranch_scc1 .Lgsync_515

	global_load_dword v1, v0, s[8:9] sc1
	s_waitcnt vmcnt(0)
	v_cmp_eq_u32_e32 vcc, 0, v1
	s_cbranch_vccnz .Lgsync_517

	s_mov_b64 s[18:19], 0
	s_mov_b64 s[16:17], -1

; __device__ __forceinline__ unsigned xb_add(unsigned* p, unsigned v) { return __hip_atomic_fetch_add(p, v, __ATOMIC_RELAXED, __HIP_MEMORY_SCOPE_AGENT); }
; __device__ __forceinline__ void xcd_barrier(const XcdBarrier& b) {
;     ...
;             if (og + 1u == (tg + 1u) * nx) xb_add(&bar[XB_TOPGEN], 1u);
.Lgsync_520:
	s_or_b64 exec, exec, s[4:5]
	s_and_saveexec_b64 s[4:5], s[8:9]
	s_cbranch_execz .Lgsync_522

; __device__ __forceinline__ unsigned xb_ld(unsigned* p)              { return __hip_atomic_load(p, __ATOMIC_RELAXED, __HIP_MEMORY_SCOPE_AGENT); }
; __device__ __forceinline__ unsigned xb_add(unsigned* p, unsigned v) { return __hip_atomic_fetch_add(p, v, __ATOMIC_RELAXED, __HIP_MEMORY_SCOPE_AGENT); }
; #define XB_SPIN(cond, bar) do { unsigned _sp = 0; while (cond) { __builtin_amdgcn_s_sleep(1); \
;     if ((++_sp & 255u) == 0u) { if (xb_ld(&(bar)[XB_TMO])) break; if (_sp > XB_SPIN_CAP) { atomicAdd(&(bar)[XB_TMO], 1u); break; } } } } while (0)
; __device__ __forceinline__ void xcd_barrier(const XcdBarrier& b) {
;     ...
;             if (og + 1u == (tg + 1u) * nx) xb_add(&bar[XB_TOPGEN], 1u);
;             else XB_SPIN(xb_ld(&bar[XB_TOPGEN]) == tg, bar);
;             __builtin_amdgcn_fence(__ATOMIC_ACQUIRE, "agent");
;             xb_add(&bar[XB_XGEN(b.x)], 1u);
	v_mov_b32_e32 v2, 1
	global_atomic_add v[0:1], v2, off
.Lgsync_522:
	s_or_b64 exec, exec, s[4:5]
	s_mov_b64 s[4:5], exec
	v_mbcnt_lo_u32_b32 v0, s4, 0
	v_mbcnt_hi_u32_b32 v0, s5, v0
	v_cmp_eq_u32_e32 vcc, 0, v0
	s_waitcnt vmcnt(0)
	buffer_inv sc1
	s_and_saveexec_b64 s[6:7], vcc
	s_cbranch_execz .Lgsync_524

; __device__ __forceinline__ unsigned xb_add(unsigned* p, unsigned v) { return __hip_atomic_fetch_add(p, v, __ATOMIC_RELAXED, __HIP_MEMORY_SCOPE_AGENT); }
; __device__ __forceinline__ void xcd_barrier(const XcdBarrier& b) {
;     ...
;             xb_add(&bar[XB_XGEN(b.x)], 1u);
	s_bcnt1_i32_b64 s4, s[4:5]
	v_mov_b32_e32 v0, 0x2000
	v_mov_b32_e32 v1, s4
	global_atomic_add v0, v1, s[2:3] offset:1024

; __device__ __forceinline__ unsigned xb_ld(unsigned* p)              { return __hip_atomic_load(p, __ATOMIC_RELAXED, __HIP_MEMORY_SCOPE_AGENT); }
; __device__ __forceinline__ unsigned xb_add(unsigned* p, unsigned v) { return __hip_atomic_fetch_add(p, v, __ATOMIC_RELAXED, __HIP_MEMORY_SCOPE_AGENT); }
; #define XB_SPIN(cond, bar) do { unsigned _sp = 0; while (cond) { __builtin_amdgcn_s_sleep(1); \
;     if ((++_sp & 255u) == 0u) { if (xb_ld(&(bar)[XB_TMO])) break; if (_sp > XB_SPIN_CAP) { atomicAdd(&(bar)[XB_TMO], 1u); break; } } } } while (0)
; __device__ __forceinline__ void xcd_barrier(const XcdBarrier& b) {
;     ...
;             xb_add(&bar[XB_XGEN(b.x)], 1u);
;             asm volatile("s_waitcnt vmcnt(0)" ::: "memory");
;         } else {
;             XB_SPIN(xb_ld(&bar[XB_XGEN(b.x)]) == gen, bar);
;             __builtin_amdgcn_fence(__ATOMIC_ACQUIRE, "agent");
;             asm volatile("s_waitcnt vmcnt(0)" ::: "memory");
;         }
;     }
;     __syncthreads();
.Lgsync_525:
	s_or_b64 exec, exec, s[0:1]
	s_waitcnt vmcnt(0)
	s_waitcnt lgkmcnt(0)
